# grid barrier flattened: non-leader WGs poll TOPGEN directly, leaders drop the XGEN bump, last leader invalidates before publishing TOPGEN (no ack wait)
# baseline (speedup 1.0000x reference)
; DI unsigned xb_ld(unsigned* p)              { return __hip_atomic_load(p, __ATOMIC_RELAXED, __HIP_MEMORY_SCOPE_AGENT); }
; DI unsigned xb_add(unsigned* p, unsigned v) { return __hip_atomic_fetch_add(p, v, __ATOMIC_RELAXED, __HIP_MEMORY_SCOPE_AGENT); }
; #define XB_SPIN(cond, bar) do { unsigned _sp = 0; while (cond) { __builtin_amdgcn_s_sleep(1); \
;     if ((++_sp & 255u) == 0u) { if (xb_ld(&(bar)[XB_TMO])) break; if (_sp > XB_SPIN_CAP) { atomicAdd(&(bar)[XB_TMO], 1u); break; } } } } while (0)
; DI void xcd_barrier(const XcdBarrier& b, int tid) {
;     ...
;         const unsigned old = xb_add(&bar[XB_XSUB(b.x)], 1u);
;         const unsigned gen = old / nloc;
;         if (old + 1u == (gen + 1u) * nloc) {
;             __builtin_amdgcn_fence(__ATOMIC_RELEASE, "agent");
;             asm volatile("s_waitcnt vmcnt(0)" ::: "memory");
;             const unsigned og = xb_add(&bar[XB_TOP], 1u);
;             const unsigned tg = og / nx;
;             if (og + 1u == (tg + 1u) * nx) xb_add(&bar[XB_TOPGEN], 1u);
;             else XB_SPIN(xb_ld(&bar[XB_TOPGEN]) == tg, bar);
;             __builtin_amdgcn_fence(__ATOMIC_ACQUIRE, "agent");
;             xb_add(&bar[XB_XGEN(b.x)], 1u);
;             asm volatile("s_waitcnt vmcnt(0)" ::: "memory");
;         } else {
;             XB_SPIN(xb_ld(&bar[XB_XGEN(b.x)]) == gen, bar);
.LBB0_107:
	s_or_b64 exec, exec, s[4:5]
	v_cvt_f32_u32_e32 v4, v2
	s_waitcnt vmcnt(0)
	v_readfirstlane_b32 s2, v3
	v_sub_u32_e32 v3, 0, v2
	v_rcp_iflag_f32_e32 v4, v4
	v_add_u32_e32 v5, s2, v1
	v_mul_f32_e32 v4, 0x4f7ffffe, v4
	v_cvt_u32_f32_e32 v4, v4
	v_mul_lo_u32 v1, v3, v4
	v_mul_hi_u32 v1, v4, v1
	v_add_u32_e32 v1, v4, v1
	v_mul_hi_u32 v1, v5, v1
	v_mul_lo_u32 v3, v1, v2
	v_sub_u32_e32 v3, v5, v3
	v_add_u32_e32 v4, 1, v1
	v_cmp_ge_u32_e32 vcc, v3, v2
	s_nop 1
	v_cndmask_b32_e32 v1, v1, v4, vcc
	v_sub_u32_e32 v4, v3, v2
	v_cndmask_b32_e32 v3, v3, v4, vcc
	v_add_u32_e32 v4, 1, v1
	v_cmp_ge_u32_e32 vcc, v3, v2
	v_add_u32_e32 v3, 1, v5
	s_nop 0
	v_cndmask_b32_e32 v1, v1, v4, vcc
	v_mul_lo_u32 v4, v2, v1
	v_add_u32_e32 v2, v4, v2
	v_cmp_ne_u32_e32 vcc, v3, v2
	s_and_saveexec_b64 s[2:3], vcc
	s_xor_b64 s[4:5], exec, s[2:3]
	s_cbranch_execz .LBB0_121
	v_readlane_b32 s2, v254, 10
	s_waitcnt lgkmcnt(0)
	v_mov_b32_e32 v0, 0
	v_readlane_b32 s3, v254, 11
	s_nop 4
	global_load_dword v2, v0, s[2:3] sc1
	s_waitcnt vmcnt(0)
	v_cmp_eq_u32_e32 vcc, v2, v1
	s_and_saveexec_b64 s[6:7], vcc
	s_cbranch_execz .LBB0_120
	s_mov_b32 s2, 1
	s_mov_b64 s[8:9], 0
	s_branch .LBB0_111

; DI unsigned xb_ld(unsigned* p)              { return __hip_atomic_load(p, __ATOMIC_RELAXED, __HIP_MEMORY_SCOPE_AGENT); }
; #define XB_SPIN(cond, bar) do { unsigned _sp = 0; while (cond) { __builtin_amdgcn_s_sleep(1); \
;     if ((++_sp & 255u) == 0u) { if (xb_ld(&(bar)[XB_TMO])) break; if (_sp > XB_SPIN_CAP) { atomicAdd(&(bar)[XB_TMO], 1u); break; } } } } while (0)
; DI void xcd_barrier(const XcdBarrier& b, int tid) {
;     ...
;             XB_SPIN(xb_ld(&bar[XB_XGEN(b.x)]) == gen, bar);
.LBB0_113:
	v_readlane_b32 s12, v254, 10
	v_readlane_b32 s13, v254, 11
	s_add_i32 s2, s2, 1
	s_mov_b64 s[14:15], -1
	s_nop 2
	global_load_dword v2, v0, s[12:13] sc1
	s_waitcnt vmcnt(0)
	v_cmp_ne_u32_e32 vcc, v2, v1
	s_orn2_b64 s[12:13], vcc, exec
	s_branch .LBB0_110

; DI unsigned xb_ld(unsigned* p)              { return __hip_atomic_load(p, __ATOMIC_RELAXED, __HIP_MEMORY_SCOPE_AGENT); }
; DI unsigned xb_add(unsigned* p, unsigned v) { return __hip_atomic_fetch_add(p, v, __ATOMIC_RELAXED, __HIP_MEMORY_SCOPE_AGENT); }
; #define XB_SPIN(cond, bar) do { unsigned _sp = 0; while (cond) { __builtin_amdgcn_s_sleep(1); \
;     if ((++_sp & 255u) == 0u) { if (xb_ld(&(bar)[XB_TMO])) break; if (_sp > XB_SPIN_CAP) { atomicAdd(&(bar)[XB_TMO], 1u); break; } } } } while (0)
; DI void xcd_barrier(const XcdBarrier& b, int tid) {
;     ...
;             __builtin_amdgcn_fence(__ATOMIC_RELEASE, "agent");
;             asm volatile("s_waitcnt vmcnt(0)" ::: "memory");
;             const unsigned og = xb_add(&bar[XB_TOP], 1u);
;             const unsigned tg = og / nx;
;             if (og + 1u == (tg + 1u) * nx) xb_add(&bar[XB_TOPGEN], 1u);
;             else XB_SPIN(xb_ld(&bar[XB_TOPGEN]) == tg, bar);
;             __builtin_amdgcn_fence(__ATOMIC_ACQUIRE, "agent");
;             xb_add(&bar[XB_XGEN(b.x)], 1u);
;             asm volatile("s_waitcnt vmcnt(0)" ::: "memory");
.LBB0_136:
	s_or_b64 exec, exec, s[4:5]
	buffer_inv sc1
	s_waitcnt vmcnt(0)
	s_and_saveexec_b64 s[4:5], s[6:7]
	s_cbranch_execz .LBB0_138
	v_mov_b32_e32 v2, 1
	global_atomic_add v[0:1], v2, off
.LBB0_138:
	s_or_b64 exec, exec, s[4:5]
	s_mov_b64 s[4:5], exec
	v_mbcnt_lo_u32_b32 v0, s4, 0
	v_mbcnt_hi_u32_b32 v0, s5, v0
	v_cmp_eq_u32_e32 vcc, 0, v0
	s_and_saveexec_b64 s[6:7], vcc
	s_cbranch_execz .LBB0_140
	s_bcnt1_i32_b64 s2, s[4:5]
	v_mov_b32_e32 v1, s2
	v_readlane_b32 s2, v254, 6
	v_mov_b32_e32 v0, 0
	v_readlane_b32 s3, v254, 7
	s_nop 4
	s_nop 0
	s_nop 0
.LBB0_140:
	s_or_b64 exec, exec, s[6:7]
	s_nop 0

; DI unsigned xb_ld(unsigned* p)              { return __hip_atomic_load(p, __ATOMIC_RELAXED, __HIP_MEMORY_SCOPE_AGENT); }
; DI unsigned xb_add(unsigned* p, unsigned v) { return __hip_atomic_fetch_add(p, v, __ATOMIC_RELAXED, __HIP_MEMORY_SCOPE_AGENT); }
; #define XB_SPIN(cond, bar) do { unsigned _sp = 0; while (cond) { __builtin_amdgcn_s_sleep(1); \
;     if ((++_sp & 255u) == 0u) { if (xb_ld(&(bar)[XB_TMO])) break; if (_sp > XB_SPIN_CAP) { atomicAdd(&(bar)[XB_TMO], 1u); break; } } } } while (0)
; DI void xcd_barrier(const XcdBarrier& b, int tid) {
;     ...
;         const unsigned old = xb_add(&bar[XB_XSUB(b.x)], 1u);
;         const unsigned gen = old / nloc;
;         if (old + 1u == (gen + 1u) * nloc) {
;             __builtin_amdgcn_fence(__ATOMIC_RELEASE, "agent");
;             asm volatile("s_waitcnt vmcnt(0)" ::: "memory");
;             const unsigned og = xb_add(&bar[XB_TOP], 1u);
;             const unsigned tg = og / nx;
;             if (og + 1u == (tg + 1u) * nx) xb_add(&bar[XB_TOPGEN], 1u);
;             else XB_SPIN(xb_ld(&bar[XB_TOPGEN]) == tg, bar);
;             __builtin_amdgcn_fence(__ATOMIC_ACQUIRE, "agent");
;             xb_add(&bar[XB_XGEN(b.x)], 1u);
;             asm volatile("s_waitcnt vmcnt(0)" ::: "memory");
;         } else {
;             XB_SPIN(xb_ld(&bar[XB_XGEN(b.x)]) == gen, bar);
.LBB0_342:
	s_or_b64 exec, exec, s[4:5]
	v_cvt_f32_u32_e32 v4, v2
	s_waitcnt vmcnt(0)
	v_readfirstlane_b32 s2, v3
	v_sub_u32_e32 v3, 0, v2
	v_rcp_iflag_f32_e32 v4, v4
	v_add_u32_e32 v5, s2, v1
	v_mul_f32_e32 v4, 0x4f7ffffe, v4
	v_cvt_u32_f32_e32 v4, v4
	v_mul_lo_u32 v1, v3, v4
	v_mul_hi_u32 v1, v4, v1
	v_add_u32_e32 v1, v4, v1
	v_mul_hi_u32 v1, v5, v1
	v_mul_lo_u32 v3, v1, v2
	v_sub_u32_e32 v3, v5, v3
	v_add_u32_e32 v4, 1, v1
	v_cmp_ge_u32_e32 vcc, v3, v2
	s_nop 1
	v_cndmask_b32_e32 v1, v1, v4, vcc
	v_sub_u32_e32 v4, v3, v2
	v_cndmask_b32_e32 v3, v3, v4, vcc
	v_add_u32_e32 v4, 1, v1
	v_cmp_ge_u32_e32 vcc, v3, v2
	v_add_u32_e32 v3, 1, v5
	s_nop 0
	v_cndmask_b32_e32 v1, v1, v4, vcc
	v_mul_lo_u32 v4, v2, v1
	v_add_u32_e32 v2, v4, v2
	v_cmp_ne_u32_e32 vcc, v3, v2
	s_and_saveexec_b64 s[4:5], vcc
	s_xor_b64 s[4:5], exec, s[4:5]
	s_cbranch_execz .LBB0_356
	v_readlane_b32 s6, v254, 10
	s_waitcnt lgkmcnt(0)
	v_mov_b32_e32 v0, 0
	v_readlane_b32 s7, v254, 11
	s_nop 4
	global_load_dword v2, v0, s[6:7] sc1
	s_waitcnt vmcnt(0)
	v_cmp_eq_u32_e32 vcc, v2, v1
	s_and_saveexec_b64 s[6:7], vcc
	s_cbranch_execz .LBB0_355
	s_mov_b32 s2, 1
	s_mov_b64 s[8:9], 0
	s_branch .LBB0_346

; DI unsigned xb_add(unsigned* p, unsigned v) { return __hip_atomic_fetch_add(p, v, __ATOMIC_RELAXED, __HIP_MEMORY_SCOPE_AGENT); }
; DI void xcd_barrier(const XcdBarrier& b, int tid) {
;     ...
;             __builtin_amdgcn_fence(__ATOMIC_ACQUIRE, "agent");
;             xb_add(&bar[XB_XGEN(b.x)], 1u);
;             asm volatile("s_waitcnt vmcnt(0)" ::: "memory");
.LBB0_373:
	s_or_b64 exec, exec, s[4:5]
	s_mov_b64 s[4:5], exec
	v_mbcnt_lo_u32_b32 v0, s4, 0
	v_mbcnt_hi_u32_b32 v0, s5, v0
	v_cmp_eq_u32_e32 vcc, 0, v0
	s_and_saveexec_b64 s[6:7], vcc
	s_cbranch_execz .LBB0_375
	s_bcnt1_i32_b64 s2, s[4:5]
	v_readlane_b32 s4, v254, 6
	v_mov_b32_e32 v0, 0
	v_mov_b32_e32 v1, s2
	v_readlane_b32 s5, v254, 7
	s_nop 4
	s_nop 0
	s_nop 0

; DI unsigned xb_ld(unsigned* p)              { return __hip_atomic_load(p, __ATOMIC_RELAXED, __HIP_MEMORY_SCOPE_AGENT); }
; DI unsigned xb_add(unsigned* p, unsigned v) { return __hip_atomic_fetch_add(p, v, __ATOMIC_RELAXED, __HIP_MEMORY_SCOPE_AGENT); }
; #define XB_SPIN(cond, bar) do { unsigned _sp = 0; while (cond) { __builtin_amdgcn_s_sleep(1); \
;     if ((++_sp & 255u) == 0u) { if (xb_ld(&(bar)[XB_TMO])) break; if (_sp > XB_SPIN_CAP) { atomicAdd(&(bar)[XB_TMO], 1u); break; } } } } while (0)
; DI void xcd_barrier(const XcdBarrier& b, int tid) {
;     ...
;         const unsigned old = xb_add(&bar[XB_XSUB(b.x)], 1u);
;         const unsigned gen = old / nloc;
;         if (old + 1u == (gen + 1u) * nloc) {
;             __builtin_amdgcn_fence(__ATOMIC_RELEASE, "agent");
;             asm volatile("s_waitcnt vmcnt(0)" ::: "memory");
;             const unsigned og = xb_add(&bar[XB_TOP], 1u);
;             const unsigned tg = og / nx;
;             if (og + 1u == (tg + 1u) * nx) xb_add(&bar[XB_TOPGEN], 1u);
;             else XB_SPIN(xb_ld(&bar[XB_TOPGEN]) == tg, bar);
;             __builtin_amdgcn_fence(__ATOMIC_ACQUIRE, "agent");
;             xb_add(&bar[XB_XGEN(b.x)], 1u);
;             asm volatile("s_waitcnt vmcnt(0)" ::: "memory");
;         } else {
;             XB_SPIN(xb_ld(&bar[XB_XGEN(b.x)]) == gen, bar);
.LBB0_1663:
	s_or_b64 exec, exec, s[6:7]
	v_cvt_f32_u32_e32 v4, v2
	s_waitcnt vmcnt(0)
	v_readfirstlane_b32 s2, v3
	v_sub_u32_e32 v3, 0, v2
	v_rcp_iflag_f32_e32 v4, v4
	v_add_u32_e32 v5, s2, v1
	v_mul_f32_e32 v4, 0x4f7ffffe, v4
	v_cvt_u32_f32_e32 v4, v4
	v_mul_lo_u32 v1, v3, v4
	v_mul_hi_u32 v1, v4, v1
	v_add_u32_e32 v1, v4, v1
	v_mul_hi_u32 v1, v5, v1
	v_mul_lo_u32 v3, v1, v2
	v_sub_u32_e32 v3, v5, v3
	v_add_u32_e32 v4, 1, v1
	v_cmp_ge_u32_e32 vcc, v3, v2
	s_nop 1
	v_cndmask_b32_e32 v1, v1, v4, vcc
	v_sub_u32_e32 v4, v3, v2
	v_cndmask_b32_e32 v3, v3, v4, vcc
	v_add_u32_e32 v4, 1, v1
	v_cmp_ge_u32_e32 vcc, v3, v2
	v_add_u32_e32 v3, 1, v5
	s_nop 0
	v_cndmask_b32_e32 v1, v1, v4, vcc
	v_mul_lo_u32 v4, v2, v1
	v_add_u32_e32 v2, v4, v2
	v_cmp_ne_u32_e32 vcc, v3, v2
	s_and_saveexec_b64 s[2:3], vcc
	s_xor_b64 s[6:7], exec, s[2:3]
	s_cbranch_execz .LBB0_1677
	v_readlane_b32 s2, v254, 10
	s_waitcnt lgkmcnt(0)
	v_mov_b32_e32 v0, 0
	v_readlane_b32 s3, v254, 11
	s_nop 4
	global_load_dword v2, v0, s[2:3] sc1
	s_waitcnt vmcnt(0)
	v_cmp_eq_u32_e32 vcc, v2, v1
	s_and_saveexec_b64 s[8:9], vcc
	s_cbranch_execz .LBB0_1676
	s_mov_b32 s2, 1
	s_mov_b64 s[10:11], 0
	s_branch .LBB0_1667

; DI unsigned xb_ld(unsigned* p)              { return __hip_atomic_load(p, __ATOMIC_RELAXED, __HIP_MEMORY_SCOPE_AGENT); }
; #define XB_SPIN(cond, bar) do { unsigned _sp = 0; while (cond) { __builtin_amdgcn_s_sleep(1); \
;     if ((++_sp & 255u) == 0u) { if (xb_ld(&(bar)[XB_TMO])) break; if (_sp > XB_SPIN_CAP) { atomicAdd(&(bar)[XB_TMO], 1u); break; } } } } while (0)
; DI void xcd_barrier(const XcdBarrier& b, int tid) {
;     ...
;             XB_SPIN(xb_ld(&bar[XB_XGEN(b.x)]) == gen, bar);
.LBB0_1669:
	v_readlane_b32 s14, v254, 10
	v_readlane_b32 s15, v254, 11
	s_add_i32 s2, s2, 1
	s_mov_b64 s[16:17], -1
	s_nop 2
	global_load_dword v2, v0, s[14:15] sc1
	s_waitcnt vmcnt(0)
	v_cmp_ne_u32_e32 vcc, v2, v1
	s_orn2_b64 s[14:15], vcc, exec
	s_branch .LBB0_1666

; DI unsigned xb_ld(unsigned* p)              { return __hip_atomic_load(p, __ATOMIC_RELAXED, __HIP_MEMORY_SCOPE_AGENT); }
; DI unsigned xb_add(unsigned* p, unsigned v) { return __hip_atomic_fetch_add(p, v, __ATOMIC_RELAXED, __HIP_MEMORY_SCOPE_AGENT); }
; #define XB_SPIN(cond, bar) do { unsigned _sp = 0; while (cond) { __builtin_amdgcn_s_sleep(1); \
;     if ((++_sp & 255u) == 0u) { if (xb_ld(&(bar)[XB_TMO])) break; if (_sp > XB_SPIN_CAP) { atomicAdd(&(bar)[XB_TMO], 1u); break; } } } } while (0)
; DI void xcd_barrier(const XcdBarrier& b, int tid) {
;     ...
;             __builtin_amdgcn_fence(__ATOMIC_RELEASE, "agent");
;             asm volatile("s_waitcnt vmcnt(0)" ::: "memory");
;             const unsigned og = xb_add(&bar[XB_TOP], 1u);
;             const unsigned tg = og / nx;
;             if (og + 1u == (tg + 1u) * nx) xb_add(&bar[XB_TOPGEN], 1u);
;             else XB_SPIN(xb_ld(&bar[XB_TOPGEN]) == tg, bar);
;             __builtin_amdgcn_fence(__ATOMIC_ACQUIRE, "agent");
;             xb_add(&bar[XB_XGEN(b.x)], 1u);
;             asm volatile("s_waitcnt vmcnt(0)" ::: "memory");
.LBB0_1692:
	s_or_b64 exec, exec, s[6:7]
	buffer_inv sc1
	s_waitcnt vmcnt(0)
	s_and_saveexec_b64 s[6:7], s[8:9]
	s_cbranch_execz .LBB0_1694
	v_mov_b32_e32 v2, 1
	global_atomic_add v[0:1], v2, off
.LBB0_1694:
	s_or_b64 exec, exec, s[6:7]
	s_mov_b64 s[6:7], exec
	v_mbcnt_lo_u32_b32 v0, s6, 0
	v_mbcnt_hi_u32_b32 v0, s7, v0
	v_cmp_eq_u32_e32 vcc, 0, v0
	s_and_saveexec_b64 s[8:9], vcc
	s_cbranch_execz .LBB0_1696
	s_bcnt1_i32_b64 s2, s[6:7]
	v_mov_b32_e32 v1, s2
	v_readlane_b32 s2, v254, 6
	v_mov_b32_e32 v0, 0
	v_readlane_b32 s3, v254, 7
	s_nop 4
	s_nop 0
	s_nop 0
.LBB0_1696:
	s_or_b64 exec, exec, s[8:9]
	s_nop 0

; DI unsigned xb_ld(unsigned* p)              { return __hip_atomic_load(p, __ATOMIC_RELAXED, __HIP_MEMORY_SCOPE_AGENT); }
; DI unsigned xb_add(unsigned* p, unsigned v) { return __hip_atomic_fetch_add(p, v, __ATOMIC_RELAXED, __HIP_MEMORY_SCOPE_AGENT); }
; #define XB_SPIN(cond, bar) do { unsigned _sp = 0; while (cond) { __builtin_amdgcn_s_sleep(1); \
;     if ((++_sp & 255u) == 0u) { if (xb_ld(&(bar)[XB_TMO])) break; if (_sp > XB_SPIN_CAP) { atomicAdd(&(bar)[XB_TMO], 1u); break; } } } } while (0)
; DI void xcd_barrier(const XcdBarrier& b, int tid) {
;     ...
;         const unsigned old = xb_add(&bar[XB_XSUB(b.x)], 1u);
;         const unsigned gen = old / nloc;
;         if (old + 1u == (gen + 1u) * nloc) {
;             __builtin_amdgcn_fence(__ATOMIC_RELEASE, "agent");
;             asm volatile("s_waitcnt vmcnt(0)" ::: "memory");
;             const unsigned og = xb_add(&bar[XB_TOP], 1u);
;             const unsigned tg = og / nx;
;             if (og + 1u == (tg + 1u) * nx) xb_add(&bar[XB_TOPGEN], 1u);
;             else XB_SPIN(xb_ld(&bar[XB_TOPGEN]) == tg, bar);
;             __builtin_amdgcn_fence(__ATOMIC_ACQUIRE, "agent");
;             xb_add(&bar[XB_XGEN(b.x)], 1u);
;             asm volatile("s_waitcnt vmcnt(0)" ::: "memory");
;         } else {
;             XB_SPIN(xb_ld(&bar[XB_XGEN(b.x)]) == gen, bar);
.LBB0_1731:
	s_or_b64 exec, exec, s[4:5]
	v_cvt_f32_u32_e32 v4, v2
	s_waitcnt vmcnt(0)
	v_readfirstlane_b32 s3, v3
	v_sub_u32_e32 v3, 0, v2
	v_rcp_iflag_f32_e32 v4, v4
	v_add_u32_e32 v5, s3, v1
	v_mul_f32_e32 v4, 0x4f7ffffe, v4
	v_cvt_u32_f32_e32 v4, v4
	v_mul_lo_u32 v1, v3, v4
	v_mul_hi_u32 v1, v4, v1
	v_add_u32_e32 v1, v4, v1
	v_mul_hi_u32 v1, v5, v1
	v_mul_lo_u32 v3, v1, v2
	v_sub_u32_e32 v3, v5, v3
	v_add_u32_e32 v4, 1, v1
	v_cmp_ge_u32_e32 vcc, v3, v2
	s_nop 1
	v_cndmask_b32_e32 v1, v1, v4, vcc
	v_sub_u32_e32 v4, v3, v2
	v_cndmask_b32_e32 v3, v3, v4, vcc
	v_add_u32_e32 v4, 1, v1
	v_cmp_ge_u32_e32 vcc, v3, v2
	v_add_u32_e32 v3, 1, v5
	s_nop 0
	v_cndmask_b32_e32 v1, v1, v4, vcc
	v_mul_lo_u32 v4, v2, v1
	v_add_u32_e32 v2, v4, v2
	v_cmp_ne_u32_e32 vcc, v3, v2
	s_and_saveexec_b64 s[4:5], vcc
	s_xor_b64 s[4:5], exec, s[4:5]
	s_cbranch_execz .LBB0_1745
	v_readlane_b32 s6, v254, 10
	s_waitcnt lgkmcnt(0)
	v_mov_b32_e32 v0, 0
	v_readlane_b32 s7, v254, 11
	s_nop 4
	global_load_dword v2, v0, s[6:7] sc1
	s_waitcnt vmcnt(0)
	v_cmp_eq_u32_e32 vcc, v2, v1
	s_and_saveexec_b64 s[6:7], vcc
	s_cbranch_execz .LBB0_1744
	s_mov_b32 s3, 1
	s_mov_b64 s[8:9], 0
	s_branch .LBB0_1735

; DI unsigned xb_ld(unsigned* p)              { return __hip_atomic_load(p, __ATOMIC_RELAXED, __HIP_MEMORY_SCOPE_AGENT); }
; #define XB_SPIN(cond, bar) do { unsigned _sp = 0; while (cond) { __builtin_amdgcn_s_sleep(1); \
;     if ((++_sp & 255u) == 0u) { if (xb_ld(&(bar)[XB_TMO])) break; if (_sp > XB_SPIN_CAP) { atomicAdd(&(bar)[XB_TMO], 1u); break; } } } } while (0)
; DI void xcd_barrier(const XcdBarrier& b, int tid) {
;     ...
;             XB_SPIN(xb_ld(&bar[XB_XGEN(b.x)]) == gen, bar);
.LBB0_1737:
	v_readlane_b32 s12, v254, 10
	v_readlane_b32 s13, v254, 11
	s_add_i32 s3, s3, 1
	s_mov_b64 s[14:15], -1
	s_nop 2
	global_load_dword v2, v0, s[12:13] sc1
	s_waitcnt vmcnt(0)
	v_cmp_ne_u32_e32 vcc, v2, v1
	s_orn2_b64 s[12:13], vcc, exec
	s_branch .LBB0_1734

; DI unsigned xb_add(unsigned* p, unsigned v) { return __hip_atomic_fetch_add(p, v, __ATOMIC_RELAXED, __HIP_MEMORY_SCOPE_AGENT); }
; DI void xcd_barrier(const XcdBarrier& b, int tid) {
;     ...
;             __builtin_amdgcn_fence(__ATOMIC_ACQUIRE, "agent");
;             xb_add(&bar[XB_XGEN(b.x)], 1u);
;             asm volatile("s_waitcnt vmcnt(0)" ::: "memory");
.LBB0_1762:
	s_or_b64 exec, exec, s[4:5]
	s_mov_b64 s[4:5], exec
	v_mbcnt_lo_u32_b32 v0, s4, 0
	v_mbcnt_hi_u32_b32 v0, s5, v0
	v_cmp_eq_u32_e32 vcc, 0, v0
	s_and_saveexec_b64 s[6:7], vcc
	s_cbranch_execz .LBB0_1764
	s_bcnt1_i32_b64 s3, s[4:5]
	v_readlane_b32 s4, v254, 6
	v_mov_b32_e32 v0, 0
	v_mov_b32_e32 v1, s3
	v_readlane_b32 s5, v254, 7
	s_nop 4
	s_nop 0
	s_nop 0
